# fused RMSNorm at the end of the w_o GEMM phase, each token tile's rows split between its two slice-free workgroups (pn = 2, 3), all four workgroups count on the tile counter
# baseline (speedup 1.0000x reference)
;     __host__ __device__ void init(int M, int N, int K, long L_) { base.init(M, N, 1, 0, K); L = L_; }
;     __host__ __device__ void init(int M0, int Mtot, int N, int K, int G_, int c_) { base.init(M0, N, G_, c_, K); nrest = ((Mtot - M0) / BM) * NN * S; nkp = (K / BK) / S; G = G_; c = c_; }
; __device__ __forceinline__ int bxl() { int b = blockIdx.x; asm volatile("" : "+s"(b)); return b; }
; __device__ __forceinline__ ArgP argp() { ArgP p = (ArgP)__builtin_amdgcn_kernarg_segment_ptr(); asm volatile("" : "+s"(p)); return p; }
; template <class Epi, class Sched, bool ALIGN_EPI = false, bool SP2 = false>
; __device__ __forceinline__ void gemm_phase(PG8_LAS unsigned char* lds, const Gemm g, const Sched& S, const Epi& E) {
;     ...
;         if constexpr (!Epi::AFTER_DRAIN) { E(acc, cur, wr, wc, fr, fq); S.done(cur); }
; __global__ void __launch_bounds__(NTHREADS, 2) fwd_megakernel(Args a_) {
;     ...
;             pg8::Gemm g{MG, (const bf16*)(wl + W_O), MP, DM, DM}; pg8::SplitOrder<4, DM / 256> S; S.init(R_META, MP, DM, DM, G, bxl());
;             pg8::EpiResid E{l == 0 ? argp()->in[I_XP] : (const float*)nullptr, H, (bf16*)(ws + WS_P + 6 * ROWBUF), DM / 64, R_META, MP - R_META};
;             pg8::gemm_phase<pg8::EpiResid, pg8::SplitOrder<4, DM / 256>, true, true>(lds, g, S, E);
.Lp4_sig:
	v_readlane_b32 s8, v255, 54
	v_readlane_b32 s9, v254, 8
	v_readlane_b32 s26, v254, 10
	v_readlane_b32 s27, v254, 11
	v_readlane_b32 s28, v255, 6
	s_cmp_eq_u32 s8, 0
	s_cbranch_scc1 .Lp4_done
	s_and_b32 s8, s9, 7
	s_lshl_b32 s8, s8, 3
	s_bfe_u32 s9, s9, 0x30003
	s_add_i32 s8, s8, s9
	s_lshl_b32 s28, s28, 6
	s_add_i32 s8, s8, s28
	s_addk_i32 s8, 0xe80
	s_lshl_b32 s8, s8, 2
	v_mov_b32_e32 v150, s8
	v_mov_b32_e32 v151, 1
	s_waitcnt vmcnt(0)
	s_mov_b64 s[28:29], exec
	s_mov_b64 exec, 1
	global_atomic_add v150, v151, s[26:27]
	s_mov_b64 exec, s[28:29]
	s_branch .Lp4_done

; __device__ __forceinline__ void rms_row(const f32x4 (&v)[4], const float* g, int lane, float& rs, f32x4 (&y)[4]) {
;     float s = 0.f;
; #pragma unroll
;     for (int j = 0; j < 4; ++j) s += (v[j].x * v[j].x + v[j].y * v[j].y) + (v[j].z * v[j].z + v[j].w * v[j].w);
;     rs = __builtin_amdgcn_rsqf(wave_sum(s) * (1.f / DM) + EPS);
; #pragma unroll
;     for (int j = 0; j < 4; ++j) { const f32x4 gv = *((const f32x4*)g + lane + 64 * j); y[j] = v[j] * rs * gv; }
; }
; template <int NSLICE> __device__ __forceinline__ void rms_phase(ArgP a, const float* g, bool final_out, int G) {
;     ...
;     for (int m = gw; m < R_META; m += 2 * NGW) {
;         const int m2 = m + NGW; const bool has2 = m2 < R_META;
;         f32x4 v[4], u[4];
;         load_bf16_row(H + (size_t)m * DM, lane, v); load_bf16_row(H + (size_t)(has2 ? m2 : m) * DM, lane, u);
;         float rs; f32x4 y[4];
;         rms_row(v, g, lane, rs, y);
;         if (!final_out) store_bf16_row(XN + (size_t)m * DM, lane, y);
.LBB0_1009:
	v_readlane_b32 s60, v255, 54
	v_readlane_b32 s61, v254, 8
	s_nop 1
	s_cmp_eq_u32 s60, 0
	s_cbranch_scc1 .Lf4_skip
	s_cmp_lt_u32 s61, 0x80
	s_cbranch_scc1 .Lf4_skip
	s_lshr_b32 s79, s61, 6
	s_sub_u32 s79, s79, 2
	s_and_b32 s64, s61, 7
	s_lshl_b32 s64, s64, 3
	s_bfe_u32 s65, s61, 0x30003
	s_add_i32 s64, s64, s65
	v_readlane_b32 s65, v255, 6
	v_readlane_b32 s68, v254, 10
	v_readlane_b32 s69, v254, 11
	v_readlane_b32 s62, v254, 2
	v_readlane_b32 s63, v254, 3
	v_readlane_b32 s60, v254, 4
	v_readlane_b32 s61, v254, 5
	s_nop 1
	s_load_dwordx2 s[66:67], s[60:61], 0x58
	s_lshl_b32 s70, s65, 6
	s_add_i32 s70, s70, s64
	s_addk_i32 s70, 0xe80
	s_lshl_b32 s70, s70, 2
	s_add_u32 s68, s68, s70
	s_addc_u32 s69, s69, 0
	s_lshl_b32 s71, s65, 12
	v_and_b32_e32 v182, 63, v193
	v_lshlrev_b32_e32 v184, 4, v182
	v_lshlrev_b32_e32 v186, 5, v182
	v_xor_b32_e32 v176, 1, v182
	v_lshlrev_b32_e32 v176, 2, v176
	v_xor_b32_e32 v177, 2, v182
	v_lshlrev_b32_e32 v177, 2, v177
	v_xor_b32_e32 v178, 4, v182
	v_lshlrev_b32_e32 v178, 2, v178
	v_xor_b32_e32 v179, 8, v182
	v_lshlrev_b32_e32 v179, 2, v179
	v_xor_b32_e32 v180, 16, v182
	v_lshlrev_b32_e32 v180, 2, v180
	v_xor_b32_e32 v181, 32, v182
	v_lshlrev_b32_e32 v181, 2, v181
	v_readfirstlane_b32 s72, v193
	s_lshr_b32 s72, s72, 6
	s_waitcnt lgkmcnt(0)
	s_add_u32 s66, s66, s71
	s_addc_u32 s67, s67, 0
	global_load_dwordx4 v[0:3], v186, s[66:67]
	global_load_dwordx4 v[4:7], v186, s[66:67] offset:16
	global_load_dwordx4 v[8:11], v186, s[66:67] offset:2048
	global_load_dwordx4 v[12:15], v186, s[66:67] offset:2064
	s_cmp_lg_u32 s72, 0
	s_cbranch_scc1 .Lf4_polled
	v_mov_b32_e32 v187, 0
	s_mov_b32 s73, 0x60
	s_mov_b64 s[74:75], exec
	s_mov_b64 exec, 1
.Lf4_poll:
	global_atomic_add v188, v187, v189, s[68:69] sc0
	s_waitcnt vmcnt(0)
	v_readfirstlane_b32 s81, v188
	s_cmp_ge_u32 s81, 32
	s_cbranch_scc1 .Lf4_pollx
	s_sleep 2
	s_sub_u32 s73, s73, 1
	s_cmp_lg_u32 s73, 0
	s_cbranch_scc1 .Lf4_poll

; template <int NSLICE> __device__ __forceinline__ void rms_phase(ArgP a, const float* g, bool final_out, int G) {
;     ...
;     for (int m = gw; m < R_META; m += 2 * NGW) {
;         const int m2 = m + NGW; const bool has2 = m2 < R_META;
;         f32x4 v[4], u[4];
;         load_bf16_row(H + (size_t)m * DM, lane, v); load_bf16_row(H + (size_t)(has2 ? m2 : m) * DM, lane, u);
;         float rs; f32x4 y[4];
;         rms_row(v, g, lane, rs, y);
;         if (!final_out) store_bf16_row(XN + (size_t)m * DM, lane, y);
;         else { float* o = a->out + O_YP + (size_t)m * DM;
; #pragma unroll
;             for (int j = 0; j < 4; ++j) *((f32x4*)o + lane + 64 * j) = y[j]; }
.Lf4_polled:
	s_barrier
	buffer_inv sc1
	s_lshl_b32 s64, s64, 19
	s_mul_i32 s72, s72, 0x8000
	s_add_u32 s64, s64, s72
	s_mul_i32 s79, s79, 0x40000
	s_add_u32 s64, s64, s79
	s_add_u32 s76, s62, 0x7580000
	s_addc_u32 s77, s63, 0
	s_add_u32 s76, s76, s64
	s_addc_u32 s77, s77, 0
	s_add_u32 s78, s62, 0x5300000
	s_addc_u32 s79, s63, 0
	s_add_u32 s78, s78, s64
	s_addc_u32 s79, s79, 0
	s_mov_b32 s80, 2
